# G2a/G2b gate epilogues: gate (and M) loads batched 8 at a time with counted vmcnt
# baseline (speedup 1.0000x reference)
; __device__ __forceinline__ unsigned cvt_pk_bf16(float lo, float hi) { unsigned r; asm volatile("v_cvt_pk_bf16_f32 %0, %1, %2" : "=v"(r) : "v"(lo), "v"(hi)); return r; }
; __device__ __forceinline__ void st8_bf16(bf16_t* p, f32x4 a, f32x4 b) { u32x4 w; w.x = cvt_pk_bf16(a[0], a[1]); w.y = cvt_pk_bf16(a[2], a[3]); w.z = cvt_pk_bf16(b[0], b[1]); w.w = cvt_pk_bf16(b[2], b[3]); *(u32x4*)p = w; }
;     __device__ __forceinline__ void operator()(AccRef acc, const pg8::Unit& u, int wr, int wc, int fr, int fq) const {
;         const int lc = u.pn * 256 + wc * 64 + fq * 8;
; #pragma unroll
;         for (int ai = 0; ai < 2; ++ai)
; #pragma unroll
;             for (int m = 0; m < 4; ++m) {
;                 const size_t row = (size_t)(u.pm * 256 + ai * 128 + wr * 64 + m * 16 + fr);
; #pragma unroll
;                 for (int bj = 0; bj < 2; ++bj) {
;                     f32x4 g0, g1; ld8_bf16(gate + row * 2048 + lc + bj * 32, g0, g1);
;                     f32x4 v0 = acc[ai][bj][m][0] * g0, v1 = acc[ai][bj][m][1] * g1;
;                     bf16_t* mp = Mb + row * 1024 + lc + bj * 32;
;                     if (ADD) { f32x4 p0, p1; ld8_bf16(mp, p0, p1); v0 += p0; v1 += p1; }
;                     st8_bf16(mp, v0, v1);
;                 }
;             }
;     }
.LBB0_501:
	v_lshl_add_u32 v142, s58, 8, v144
	v_lshl_or_b32 v140, s57, 8, v162
	v_ashrrev_i32_e32 v143, 31, v142
	v_ashrrev_i32_e32 v141, 31, v140
	v_lshlrev_b64 v[140:141], 1, v[140:141]
	s_andn2_b64 vcc, exec, s[6:7]
	s_mov_b64 s[6:7], -1
	v_lshlrev_b64 v[212:213], 12, v[142:143]
	v_lshlrev_b64 v[220:221], 11, v[142:143]
	v_lshl_add_u64 v[212:213], s[94:95], 0, v[212:213]
	v_lshl_add_u64 v[220:221], s[20:21], 0, v[220:221]
	v_lshl_add_u64 v[212:213], v[212:213], 0, v[140:141]
	v_lshl_add_u64 v[220:221], v[220:221], 0, v[140:141]
	v_add_u32_e32 v222, 0x10, v142
	v_ashrrev_i32_e32 v223, 31, v222
	v_lshlrev_b64 v[214:215], 12, v[222:223]
	v_lshlrev_b64 v[222:223], 11, v[222:223]
	v_lshl_add_u64 v[214:215], s[94:95], 0, v[214:215]
	v_lshl_add_u64 v[222:223], s[20:21], 0, v[222:223]
	v_lshl_add_u64 v[214:215], v[214:215], 0, v[140:141]
	v_lshl_add_u64 v[222:223], v[222:223], 0, v[140:141]
	v_add_u32_e32 v224, 0x20, v142
	v_ashrrev_i32_e32 v225, 31, v224
	v_lshlrev_b64 v[216:217], 12, v[224:225]
	v_lshlrev_b64 v[224:225], 11, v[224:225]
	v_lshl_add_u64 v[216:217], s[94:95], 0, v[216:217]
	v_lshl_add_u64 v[224:225], s[20:21], 0, v[224:225]
	v_lshl_add_u64 v[216:217], v[216:217], 0, v[140:141]
	v_lshl_add_u64 v[224:225], v[224:225], 0, v[140:141]
	v_add_u32_e32 v226, 0x30, v142
	v_ashrrev_i32_e32 v227, 31, v226
	v_lshlrev_b64 v[218:219], 12, v[226:227]
	v_lshlrev_b64 v[226:227], 11, v[226:227]
	v_lshl_add_u64 v[218:219], s[94:95], 0, v[218:219]
	v_lshl_add_u64 v[226:227], s[20:21], 0, v[226:227]
	v_lshl_add_u64 v[218:219], v[218:219], 0, v[140:141]
	v_lshl_add_u64 v[226:227], v[226:227], 0, v[140:141]
	global_load_dwordx4 v[164:167], v[212:213], off
	global_load_dwordx4 v[168:171], v[212:213], off offset:64
	global_load_dwordx4 v[172:175], v[214:215], off
	global_load_dwordx4 v[176:179], v[214:215], off offset:64
	global_load_dwordx4 v[180:183], v[216:217], off
	global_load_dwordx4 v[184:187], v[216:217], off offset:64
	global_load_dwordx4 v[188:191], v[218:219], off
	global_load_dwordx4 v[192:195], v[218:219], off offset:64
	s_waitcnt vmcnt(0)
	v_lshlrev_b32_e32 v236, 16, v164
	v_and_b32_e32 v237, 0xffff0000, v164
	v_pk_mul_f32 v[126:127], v[126:127], v[236:237]
	v_lshlrev_b32_e32 v236, 16, v165
	v_and_b32_e32 v237, 0xffff0000, v165
	v_pk_mul_f32 v[128:129], v[128:129], v[236:237]
	v_lshlrev_b32_e32 v236, 16, v166
	v_and_b32_e32 v237, 0xffff0000, v166
	v_pk_mul_f32 v[122:123], v[122:123], v[236:237]
	v_lshlrev_b32_e32 v236, 16, v167
	v_and_b32_e32 v237, 0xffff0000, v167
	v_pk_mul_f32 v[124:125], v[124:125], v[236:237]
	v_cvt_pk_bf16_f32 v126, v126, v127
	v_cvt_pk_bf16_f32 v127, v128, v129
	v_cvt_pk_bf16_f32 v128, v122, v123
	v_cvt_pk_bf16_f32 v129, v124, v125
	v_lshlrev_b32_e32 v236, 16, v168
	v_and_b32_e32 v237, 0xffff0000, v168
	v_pk_mul_f32 v[114:115], v[114:115], v[236:237]
	v_lshlrev_b32_e32 v236, 16, v169
	v_and_b32_e32 v237, 0xffff0000, v169
	v_pk_mul_f32 v[116:117], v[116:117], v[236:237]
	v_lshlrev_b32_e32 v236, 16, v170
	v_and_b32_e32 v237, 0xffff0000, v170
	v_pk_mul_f32 v[110:111], v[110:111], v[236:237]
	v_lshlrev_b32_e32 v236, 16, v171
	v_and_b32_e32 v237, 0xffff0000, v171
	v_pk_mul_f32 v[112:113], v[112:113], v[236:237]
	v_cvt_pk_bf16_f32 v114, v114, v115
	v_cvt_pk_bf16_f32 v115, v116, v117
	v_cvt_pk_bf16_f32 v116, v110, v111
	v_cvt_pk_bf16_f32 v117, v112, v113
	v_lshlrev_b32_e32 v236, 16, v172
	v_and_b32_e32 v237, 0xffff0000, v172
	v_pk_mul_f32 v[118:119], v[118:119], v[236:237]
	v_lshlrev_b32_e32 v236, 16, v173
	v_and_b32_e32 v237, 0xffff0000, v173
	v_pk_mul_f32 v[120:121], v[120:121], v[236:237]
	v_lshlrev_b32_e32 v236, 16, v174
	v_and_b32_e32 v237, 0xffff0000, v174
	v_pk_mul_f32 v[106:107], v[106:107], v[236:237]
	v_lshlrev_b32_e32 v236, 16, v175
	v_and_b32_e32 v237, 0xffff0000, v175
	v_pk_mul_f32 v[108:109], v[108:109], v[236:237]
	v_cvt_pk_bf16_f32 v118, v118, v119
	v_cvt_pk_bf16_f32 v119, v120, v121
	v_cvt_pk_bf16_f32 v120, v106, v107
	v_cvt_pk_bf16_f32 v121, v108, v109
	v_lshlrev_b32_e32 v236, 16, v176
	v_and_b32_e32 v237, 0xffff0000, v176
	v_pk_mul_f32 v[98:99], v[98:99], v[236:237]
	v_lshlrev_b32_e32 v236, 16, v177
	v_and_b32_e32 v237, 0xffff0000, v177
	v_pk_mul_f32 v[100:101], v[100:101], v[236:237]
	v_lshlrev_b32_e32 v236, 16, v178
	v_and_b32_e32 v237, 0xffff0000, v178
	v_pk_mul_f32 v[94:95], v[94:95], v[236:237]
	v_lshlrev_b32_e32 v236, 16, v179
	v_and_b32_e32 v237, 0xffff0000, v179
	v_pk_mul_f32 v[96:97], v[96:97], v[236:237]
	v_cvt_pk_bf16_f32 v98, v98, v99
	v_cvt_pk_bf16_f32 v99, v100, v101
	v_cvt_pk_bf16_f32 v100, v94, v95
	v_cvt_pk_bf16_f32 v101, v96, v97
	v_lshlrev_b32_e32 v236, 16, v180
	v_and_b32_e32 v237, 0xffff0000, v180
	v_pk_mul_f32 v[102:103], v[102:103], v[236:237]
	v_lshlrev_b32_e32 v236, 16, v181
	v_and_b32_e32 v237, 0xffff0000, v181
	v_pk_mul_f32 v[104:105], v[104:105], v[236:237]
	v_lshlrev_b32_e32 v236, 16, v182
	v_and_b32_e32 v237, 0xffff0000, v182
	v_pk_mul_f32 v[90:91], v[90:91], v[236:237]
	v_lshlrev_b32_e32 v236, 16, v183
	v_and_b32_e32 v237, 0xffff0000, v183
	v_pk_mul_f32 v[92:93], v[92:93], v[236:237]
	v_cvt_pk_bf16_f32 v102, v102, v103
	v_cvt_pk_bf16_f32 v103, v104, v105
	v_cvt_pk_bf16_f32 v104, v90, v91
	v_cvt_pk_bf16_f32 v105, v92, v93
	v_lshlrev_b32_e32 v236, 16, v184
	v_and_b32_e32 v237, 0xffff0000, v184
	v_pk_mul_f32 v[82:83], v[82:83], v[236:237]
	v_lshlrev_b32_e32 v236, 16, v185
	v_and_b32_e32 v237, 0xffff0000, v185
	v_pk_mul_f32 v[84:85], v[84:85], v[236:237]
	v_lshlrev_b32_e32 v236, 16, v186
	v_and_b32_e32 v237, 0xffff0000, v186
	v_pk_mul_f32 v[78:79], v[78:79], v[236:237]
	v_lshlrev_b32_e32 v236, 16, v187
	v_and_b32_e32 v237, 0xffff0000, v187
	v_pk_mul_f32 v[80:81], v[80:81], v[236:237]
; __device__ __forceinline__ unsigned cvt_pk_bf16(float lo, float hi) { unsigned r; asm volatile("v_cvt_pk_bf16_f32 %0, %1, %2" : "=v"(r) : "v"(lo), "v"(hi)); return r; }
; __device__ __forceinline__ void st8_bf16(bf16_t* p, f32x4 a, f32x4 b) { u32x4 w; w.x = cvt_pk_bf16(a[0], a[1]); w.y = cvt_pk_bf16(a[2], a[3]); w.z = cvt_pk_bf16(b[0], b[1]); w.w = cvt_pk_bf16(b[2], b[3]); *(u32x4*)p = w; }
;     __device__ __forceinline__ void operator()(AccRef acc, const pg8::Unit& u, int wr, int wc, int fr, int fq) const {
;         const int lc = u.pn * 256 + wc * 64 + fq * 8;
; #pragma unroll
;         for (int ai = 0; ai < 2; ++ai)
; #pragma unroll
;             for (int m = 0; m < 4; ++m) {
;                 const size_t row = (size_t)(u.pm * 256 + ai * 128 + wr * 64 + m * 16 + fr);
; #pragma unroll
;                 for (int bj = 0; bj < 2; ++bj) {
;                     f32x4 g0, g1; ld8_bf16(gate + row * 2048 + lc + bj * 32, g0, g1);
;                     f32x4 v0 = acc[ai][bj][m][0] * g0, v1 = acc[ai][bj][m][1] * g1;
;                     bf16_t* mp = Mb + row * 1024 + lc + bj * 32;
;                     if (ADD) { f32x4 p0, p1; ld8_bf16(mp, p0, p1); v0 += p0; v1 += p1; }
;                     st8_bf16(mp, v0, v1);
;                 }
;             }
;     }
	v_cvt_pk_bf16_f32 v82, v82, v83
	v_cvt_pk_bf16_f32 v83, v84, v85
	v_cvt_pk_bf16_f32 v84, v78, v79
	v_cvt_pk_bf16_f32 v85, v80, v81
	v_lshlrev_b32_e32 v236, 16, v188
	v_and_b32_e32 v237, 0xffff0000, v188
	v_pk_mul_f32 v[86:87], v[86:87], v[236:237]
	v_lshlrev_b32_e32 v236, 16, v189
	v_and_b32_e32 v237, 0xffff0000, v189
	v_pk_mul_f32 v[88:89], v[88:89], v[236:237]
	v_lshlrev_b32_e32 v236, 16, v190
	v_and_b32_e32 v237, 0xffff0000, v190
	v_pk_mul_f32 v[74:75], v[74:75], v[236:237]
	v_lshlrev_b32_e32 v236, 16, v191
	v_and_b32_e32 v237, 0xffff0000, v191
	v_pk_mul_f32 v[76:77], v[76:77], v[236:237]
	v_cvt_pk_bf16_f32 v86, v86, v87
	v_cvt_pk_bf16_f32 v87, v88, v89
	v_cvt_pk_bf16_f32 v88, v74, v75
	v_cvt_pk_bf16_f32 v89, v76, v77
	v_lshlrev_b32_e32 v236, 16, v192
	v_and_b32_e32 v237, 0xffff0000, v192
	v_pk_mul_f32 v[70:71], v[70:71], v[236:237]
	v_lshlrev_b32_e32 v236, 16, v193
	v_and_b32_e32 v237, 0xffff0000, v193
	v_pk_mul_f32 v[72:73], v[72:73], v[236:237]
	v_lshlrev_b32_e32 v236, 16, v194
	v_and_b32_e32 v237, 0xffff0000, v194
	v_pk_mul_f32 v[66:67], v[66:67], v[236:237]
	v_lshlrev_b32_e32 v236, 16, v195
	v_and_b32_e32 v237, 0xffff0000, v195
	v_pk_mul_f32 v[68:69], v[68:69], v[236:237]
	v_cvt_pk_bf16_f32 v70, v70, v71
	v_cvt_pk_bf16_f32 v71, v72, v73
	v_cvt_pk_bf16_f32 v72, v66, v67
	v_cvt_pk_bf16_f32 v73, v68, v69
	v_add_u32_e32 v228, 0x80, v142
	v_ashrrev_i32_e32 v229, 31, v228
	v_lshlrev_b64 v[212:213], 12, v[228:229]
	v_lshlrev_b64 v[228:229], 11, v[228:229]
	v_lshl_add_u64 v[212:213], s[94:95], 0, v[212:213]
	v_lshl_add_u64 v[228:229], s[20:21], 0, v[228:229]
	v_lshl_add_u64 v[212:213], v[212:213], 0, v[140:141]
	v_lshl_add_u64 v[228:229], v[228:229], 0, v[140:141]
	v_add_u32_e32 v230, 0x90, v142
	v_ashrrev_i32_e32 v231, 31, v230
	v_lshlrev_b64 v[214:215], 12, v[230:231]
	v_lshlrev_b64 v[230:231], 11, v[230:231]
	v_lshl_add_u64 v[214:215], s[94:95], 0, v[214:215]
	v_lshl_add_u64 v[230:231], s[20:21], 0, v[230:231]
	v_lshl_add_u64 v[214:215], v[214:215], 0, v[140:141]
	v_lshl_add_u64 v[230:231], v[230:231], 0, v[140:141]
	v_add_u32_e32 v232, 0xa0, v142
	v_ashrrev_i32_e32 v233, 31, v232
	v_lshlrev_b64 v[216:217], 12, v[232:233]
	v_lshlrev_b64 v[232:233], 11, v[232:233]
	v_lshl_add_u64 v[216:217], s[94:95], 0, v[216:217]
	v_lshl_add_u64 v[232:233], s[20:21], 0, v[232:233]
	v_lshl_add_u64 v[216:217], v[216:217], 0, v[140:141]
	v_lshl_add_u64 v[232:233], v[232:233], 0, v[140:141]
	v_add_u32_e32 v234, 0xb0, v142
	v_ashrrev_i32_e32 v235, 31, v234
	v_lshlrev_b64 v[218:219], 12, v[234:235]
	v_lshlrev_b64 v[234:235], 11, v[234:235]
	v_lshl_add_u64 v[218:219], s[94:95], 0, v[218:219]
	v_lshl_add_u64 v[234:235], s[20:21], 0, v[234:235]
	v_lshl_add_u64 v[218:219], v[218:219], 0, v[140:141]
	v_lshl_add_u64 v[234:235], v[234:235], 0, v[140:141]
	global_load_dwordx4 v[164:167], v[212:213], off
	global_load_dwordx4 v[168:171], v[212:213], off offset:64
	global_load_dwordx4 v[172:175], v[214:215], off
	global_load_dwordx4 v[176:179], v[214:215], off offset:64
	global_load_dwordx4 v[180:183], v[216:217], off
	global_load_dwordx4 v[184:187], v[216:217], off offset:64
	global_load_dwordx4 v[188:191], v[218:219], off
	global_load_dwordx4 v[192:195], v[218:219], off offset:64
	global_store_dwordx4 v[220:221], v[126:129], off
	global_store_dwordx4 v[220:221], v[114:117], off offset:64
	global_store_dwordx4 v[222:223], v[118:121], off
	global_store_dwordx4 v[222:223], v[98:101], off offset:64
	global_store_dwordx4 v[224:225], v[102:105], off
	global_store_dwordx4 v[224:225], v[82:85], off offset:64
	global_store_dwordx4 v[226:227], v[86:89], off
	global_store_dwordx4 v[226:227], v[70:73], off offset:64
	s_waitcnt vmcnt(8)
; __device__ __forceinline__ unsigned cvt_pk_bf16(float lo, float hi) { unsigned r; asm volatile("v_cvt_pk_bf16_f32 %0, %1, %2" : "=v"(r) : "v"(lo), "v"(hi)); return r; }
; __device__ __forceinline__ void st8_bf16(bf16_t* p, f32x4 a, f32x4 b) { u32x4 w; w.x = cvt_pk_bf16(a[0], a[1]); w.y = cvt_pk_bf16(a[2], a[3]); w.z = cvt_pk_bf16(b[0], b[1]); w.w = cvt_pk_bf16(b[2], b[3]); *(u32x4*)p = w; }
;     __device__ __forceinline__ void operator()(AccRef acc, const pg8::Unit& u, int wr, int wc, int fr, int fq) const {
;         const int lc = u.pn * 256 + wc * 64 + fq * 8;
; #pragma unroll
;         for (int ai = 0; ai < 2; ++ai)
; #pragma unroll
;             for (int m = 0; m < 4; ++m) {
;                 const size_t row = (size_t)(u.pm * 256 + ai * 128 + wr * 64 + m * 16 + fr);
; #pragma unroll
;                 for (int bj = 0; bj < 2; ++bj) {
;                     f32x4 g0, g1; ld8_bf16(gate + row * 2048 + lc + bj * 32, g0, g1);
;                     f32x4 v0 = acc[ai][bj][m][0] * g0, v1 = acc[ai][bj][m][1] * g1;
;                     bf16_t* mp = Mb + row * 1024 + lc + bj * 32;
;                     if (ADD) { f32x4 p0, p1; ld8_bf16(mp, p0, p1); v0 += p0; v1 += p1; }
;                     st8_bf16(mp, v0, v1);
;                 }
;             }
;     }
	v_lshlrev_b32_e32 v236, 16, v164
	v_and_b32_e32 v237, 0xffff0000, v164
	v_pk_mul_f32 v[62:63], v[62:63], v[236:237]
	v_lshlrev_b32_e32 v236, 16, v165
	v_and_b32_e32 v237, 0xffff0000, v165
	v_pk_mul_f32 v[64:65], v[64:65], v[236:237]
	v_lshlrev_b32_e32 v236, 16, v166
	v_and_b32_e32 v237, 0xffff0000, v166
	v_pk_mul_f32 v[58:59], v[58:59], v[236:237]
	v_lshlrev_b32_e32 v236, 16, v167
	v_and_b32_e32 v237, 0xffff0000, v167
	v_pk_mul_f32 v[60:61], v[60:61], v[236:237]
	v_cvt_pk_bf16_f32 v62, v62, v63
	v_cvt_pk_bf16_f32 v63, v64, v65
	v_cvt_pk_bf16_f32 v64, v58, v59
	v_cvt_pk_bf16_f32 v65, v60, v61
	v_lshlrev_b32_e32 v236, 16, v168
	v_and_b32_e32 v237, 0xffff0000, v168
	v_pk_mul_f32 v[50:51], v[50:51], v[236:237]
	v_lshlrev_b32_e32 v236, 16, v169
	v_and_b32_e32 v237, 0xffff0000, v169
	v_pk_mul_f32 v[52:53], v[52:53], v[236:237]
	v_lshlrev_b32_e32 v236, 16, v170
	v_and_b32_e32 v237, 0xffff0000, v170
	v_pk_mul_f32 v[46:47], v[46:47], v[236:237]
	v_lshlrev_b32_e32 v236, 16, v171
	v_and_b32_e32 v237, 0xffff0000, v171
	v_pk_mul_f32 v[48:49], v[48:49], v[236:237]
	v_cvt_pk_bf16_f32 v50, v50, v51
	v_cvt_pk_bf16_f32 v51, v52, v53
	v_cvt_pk_bf16_f32 v52, v46, v47
	v_cvt_pk_bf16_f32 v53, v48, v49
	v_lshlrev_b32_e32 v236, 16, v172
	v_and_b32_e32 v237, 0xffff0000, v172
	v_pk_mul_f32 v[54:55], v[54:55], v[236:237]
	v_lshlrev_b32_e32 v236, 16, v173
	v_and_b32_e32 v237, 0xffff0000, v173
	v_pk_mul_f32 v[56:57], v[56:57], v[236:237]
	v_lshlrev_b32_e32 v236, 16, v174
	v_and_b32_e32 v237, 0xffff0000, v174
	v_pk_mul_f32 v[42:43], v[42:43], v[236:237]
	v_lshlrev_b32_e32 v236, 16, v175
	v_and_b32_e32 v237, 0xffff0000, v175
	v_pk_mul_f32 v[44:45], v[44:45], v[236:237]
	v_cvt_pk_bf16_f32 v54, v54, v55
	v_cvt_pk_bf16_f32 v55, v56, v57
	v_cvt_pk_bf16_f32 v56, v42, v43
	v_cvt_pk_bf16_f32 v57, v44, v45
	v_lshlrev_b32_e32 v236, 16, v176
	v_and_b32_e32 v237, 0xffff0000, v176
	v_pk_mul_f32 v[34:35], v[34:35], v[236:237]
	v_lshlrev_b32_e32 v236, 16, v177
	v_and_b32_e32 v237, 0xffff0000, v177
	v_pk_mul_f32 v[36:37], v[36:37], v[236:237]
	v_lshlrev_b32_e32 v236, 16, v178
	v_and_b32_e32 v237, 0xffff0000, v178
	v_pk_mul_f32 v[30:31], v[30:31], v[236:237]
	v_lshlrev_b32_e32 v236, 16, v179
	v_and_b32_e32 v237, 0xffff0000, v179
	v_pk_mul_f32 v[32:33], v[32:33], v[236:237]
	v_cvt_pk_bf16_f32 v34, v34, v35
	v_cvt_pk_bf16_f32 v35, v36, v37
	v_cvt_pk_bf16_f32 v36, v30, v31
	v_cvt_pk_bf16_f32 v37, v32, v33
	v_lshlrev_b32_e32 v236, 16, v180
	v_and_b32_e32 v237, 0xffff0000, v180
	v_pk_mul_f32 v[38:39], v[38:39], v[236:237]
	v_lshlrev_b32_e32 v236, 16, v181
	v_and_b32_e32 v237, 0xffff0000, v181
	v_pk_mul_f32 v[40:41], v[40:41], v[236:237]
	v_lshlrev_b32_e32 v236, 16, v182
	v_and_b32_e32 v237, 0xffff0000, v182
	v_pk_mul_f32 v[26:27], v[26:27], v[236:237]
	v_lshlrev_b32_e32 v236, 16, v183
	v_and_b32_e32 v237, 0xffff0000, v183
	v_pk_mul_f32 v[28:29], v[28:29], v[236:237]
	v_cvt_pk_bf16_f32 v38, v38, v39
	v_cvt_pk_bf16_f32 v39, v40, v41
	v_cvt_pk_bf16_f32 v40, v26, v27
	v_cvt_pk_bf16_f32 v41, v28, v29
	v_lshlrev_b32_e32 v236, 16, v184
	v_and_b32_e32 v237, 0xffff0000, v184
	v_pk_mul_f32 v[18:19], v[18:19], v[236:237]
	v_lshlrev_b32_e32 v236, 16, v185
	v_and_b32_e32 v237, 0xffff0000, v185
	v_pk_mul_f32 v[20:21], v[20:21], v[236:237]
	v_lshlrev_b32_e32 v236, 16, v186
	v_and_b32_e32 v237, 0xffff0000, v186
	v_pk_mul_f32 v[14:15], v[14:15], v[236:237]
	v_lshlrev_b32_e32 v236, 16, v187
	v_and_b32_e32 v237, 0xffff0000, v187
	v_pk_mul_f32 v[16:17], v[16:17], v[236:237]
	v_cvt_pk_bf16_f32 v18, v18, v19
	v_cvt_pk_bf16_f32 v19, v20, v21
	v_cvt_pk_bf16_f32 v20, v14, v15
	v_cvt_pk_bf16_f32 v21, v16, v17
	v_lshlrev_b32_e32 v236, 16, v188
	v_and_b32_e32 v237, 0xffff0000, v188
	v_pk_mul_f32 v[22:23], v[22:23], v[236:237]
	v_lshlrev_b32_e32 v236, 16, v189
	v_and_b32_e32 v237, 0xffff0000, v189
	v_pk_mul_f32 v[24:25], v[24:25], v[236:237]
	v_lshlrev_b32_e32 v236, 16, v190
	v_and_b32_e32 v237, 0xffff0000, v190
	v_pk_mul_f32 v[10:11], v[10:11], v[236:237]
	v_lshlrev_b32_e32 v236, 16, v191
	v_and_b32_e32 v237, 0xffff0000, v191
	v_pk_mul_f32 v[12:13], v[12:13], v[236:237]
	v_cvt_pk_bf16_f32 v22, v22, v23
	v_cvt_pk_bf16_f32 v23, v24, v25
	v_cvt_pk_bf16_f32 v24, v10, v11
	v_cvt_pk_bf16_f32 v25, v12, v13
	v_lshlrev_b32_e32 v236, 16, v192
	v_and_b32_e32 v237, 0xffff0000, v192
	v_pk_mul_f32 v[6:7], v[6:7], v[236:237]
	v_lshlrev_b32_e32 v236, 16, v193
	v_and_b32_e32 v237, 0xffff0000, v193
	v_pk_mul_f32 v[8:9], v[8:9], v[236:237]
	v_lshlrev_b32_e32 v236, 16, v194
	v_and_b32_e32 v237, 0xffff0000, v194
	v_pk_mul_f32 v[2:3], v[2:3], v[236:237]
	v_lshlrev_b32_e32 v236, 16, v195
	v_and_b32_e32 v237, 0xffff0000, v195
	v_pk_mul_f32 v[4:5], v[4:5], v[236:237]
	v_cvt_pk_bf16_f32 v6, v6, v7
	v_cvt_pk_bf16_f32 v7, v8, v9
	v_cvt_pk_bf16_f32 v8, v2, v3
	v_cvt_pk_bf16_f32 v9, v4, v5
	global_store_dwordx4 v[228:229], v[62:65], off
	global_store_dwordx4 v[228:229], v[50:53], off offset:64
	global_store_dwordx4 v[230:231], v[54:57], off
	global_store_dwordx4 v[230:231], v[34:37], off offset:64
	global_store_dwordx4 v[232:233], v[38:41], off
	global_store_dwordx4 v[232:233], v[18:21], off offset:64
	global_store_dwordx4 v[234:235], v[22:25], off
	global_store_dwordx4 v[234:235], v[6:9], off offset:64
	s_cbranch_vccnz .LBB0_490
	s_andn2_b64 vcc, exec, s[0:1]
	s_cbranch_vccnz .LBB0_489
	s_barrier
	s_branch .LBB0_489

; __device__ __forceinline__ unsigned cvt_pk_bf16(float lo, float hi) { unsigned r; asm volatile("v_cvt_pk_bf16_f32 %0, %1, %2" : "=v"(r) : "v"(lo), "v"(hi)); return r; }
; __device__ __forceinline__ void st8_bf16(bf16_t* p, f32x4 a, f32x4 b) { u32x4 w; w.x = cvt_pk_bf16(a[0], a[1]); w.y = cvt_pk_bf16(a[2], a[3]); w.z = cvt_pk_bf16(b[0], b[1]); w.w = cvt_pk_bf16(b[2], b[3]); *(u32x4*)p = w; }
;     __device__ __forceinline__ void operator()(AccRef acc, const pg8::Unit& u, int wr, int wc, int fr, int fq) const {
;         const int lc = u.pn * 256 + wc * 64 + fq * 8;
; #pragma unroll
;         for (int ai = 0; ai < 2; ++ai)
; #pragma unroll
;             for (int m = 0; m < 4; ++m) {
;                 const size_t row = (size_t)(u.pm * 256 + ai * 128 + wr * 64 + m * 16 + fr);
; #pragma unroll
;                 for (int bj = 0; bj < 2; ++bj) {
;                     f32x4 g0, g1; ld8_bf16(gate + row * 2048 + lc + bj * 32, g0, g1);
;                     f32x4 v0 = acc[ai][bj][m][0] * g0, v1 = acc[ai][bj][m][1] * g1;
;                     bf16_t* mp = Mb + row * 1024 + lc + bj * 32;
;                     if (ADD) { f32x4 p0, p1; ld8_bf16(mp, p0, p1); v0 += p0; v1 += p1; }
;                     st8_bf16(mp, v0, v1);
;                 }
;             }
;     }
.LBB0_521:
	v_lshl_add_u32 v142, s56, 8, v144
	v_lshl_or_b32 v140, s55, 8, v162
	v_ashrrev_i32_e32 v143, 31, v142
	v_ashrrev_i32_e32 v141, 31, v140
	v_lshlrev_b64 v[140:141], 1, v[140:141]
	s_andn2_b64 vcc, exec, s[4:5]
	s_mov_b64 s[4:5], -1
	v_lshlrev_b64 v[212:213], 12, v[142:143]
	v_lshlrev_b64 v[220:221], 11, v[142:143]
	v_lshl_add_u64 v[212:213], s[84:85], 0, v[212:213]
	v_lshl_add_u64 v[220:221], s[20:21], 0, v[220:221]
	v_lshl_add_u64 v[212:213], v[212:213], 0, v[140:141]
	v_lshl_add_u64 v[220:221], v[220:221], 0, v[140:141]
	v_add_u32_e32 v222, 0x10, v142
	v_ashrrev_i32_e32 v223, 31, v222
	v_lshlrev_b64 v[214:215], 12, v[222:223]
	v_lshlrev_b64 v[222:223], 11, v[222:223]
	v_lshl_add_u64 v[214:215], s[84:85], 0, v[214:215]
	v_lshl_add_u64 v[222:223], s[20:21], 0, v[222:223]
	v_lshl_add_u64 v[214:215], v[214:215], 0, v[140:141]
	v_lshl_add_u64 v[222:223], v[222:223], 0, v[140:141]
	global_load_dwordx4 v[164:167], v[212:213], off
	global_load_dwordx4 v[168:171], v[220:221], off
	global_load_dwordx4 v[172:175], v[212:213], off offset:64
	global_load_dwordx4 v[176:179], v[220:221], off offset:64
	global_load_dwordx4 v[180:183], v[214:215], off
	global_load_dwordx4 v[184:187], v[222:223], off
	global_load_dwordx4 v[188:191], v[214:215], off offset:64
	global_load_dwordx4 v[192:195], v[222:223], off offset:64
	s_waitcnt vmcnt(0)
	v_lshlrev_b32_e32 v236, 16, v164
	v_and_b32_e32 v237, 0xffff0000, v164
	v_lshlrev_b32_e32 v238, 16, v168
	v_and_b32_e32 v239, 0xffff0000, v168
	v_pk_fma_f32 v[126:127], v[126:127], v[236:237], v[238:239]
	v_lshlrev_b32_e32 v236, 16, v165
	v_and_b32_e32 v237, 0xffff0000, v165
	v_lshlrev_b32_e32 v238, 16, v169
	v_and_b32_e32 v239, 0xffff0000, v169
	v_pk_fma_f32 v[128:129], v[128:129], v[236:237], v[238:239]
	v_lshlrev_b32_e32 v236, 16, v166
	v_and_b32_e32 v237, 0xffff0000, v166
	v_lshlrev_b32_e32 v238, 16, v170
	v_and_b32_e32 v239, 0xffff0000, v170
	v_pk_fma_f32 v[122:123], v[122:123], v[236:237], v[238:239]
	v_lshlrev_b32_e32 v236, 16, v167
	v_and_b32_e32 v237, 0xffff0000, v167
	v_lshlrev_b32_e32 v238, 16, v171
	v_and_b32_e32 v239, 0xffff0000, v171
	v_pk_fma_f32 v[124:125], v[124:125], v[236:237], v[238:239]
	v_cvt_pk_bf16_f32 v126, v126, v127
	v_cvt_pk_bf16_f32 v127, v128, v129
	v_cvt_pk_bf16_f32 v128, v122, v123
	v_cvt_pk_bf16_f32 v129, v124, v125
	v_lshlrev_b32_e32 v236, 16, v172
	v_and_b32_e32 v237, 0xffff0000, v172
	v_lshlrev_b32_e32 v238, 16, v176
	v_and_b32_e32 v239, 0xffff0000, v176
	v_pk_fma_f32 v[118:119], v[118:119], v[236:237], v[238:239]
	v_lshlrev_b32_e32 v236, 16, v173
	v_and_b32_e32 v237, 0xffff0000, v173
	v_lshlrev_b32_e32 v238, 16, v177
	v_and_b32_e32 v239, 0xffff0000, v177
	v_pk_fma_f32 v[120:121], v[120:121], v[236:237], v[238:239]
	v_lshlrev_b32_e32 v236, 16, v174
	v_and_b32_e32 v237, 0xffff0000, v174
	v_lshlrev_b32_e32 v238, 16, v178
	v_and_b32_e32 v239, 0xffff0000, v178
	v_pk_fma_f32 v[114:115], v[114:115], v[236:237], v[238:239]
	v_lshlrev_b32_e32 v236, 16, v175
	v_and_b32_e32 v237, 0xffff0000, v175
	v_lshlrev_b32_e32 v238, 16, v179
	v_and_b32_e32 v239, 0xffff0000, v179
	v_pk_fma_f32 v[116:117], v[116:117], v[236:237], v[238:239]
	v_cvt_pk_bf16_f32 v118, v118, v119
	v_cvt_pk_bf16_f32 v119, v120, v121
	v_cvt_pk_bf16_f32 v120, v114, v115
	v_cvt_pk_bf16_f32 v121, v116, v117
	v_lshlrev_b32_e32 v236, 16, v180
	v_and_b32_e32 v237, 0xffff0000, v180
	v_lshlrev_b32_e32 v238, 16, v184
	v_and_b32_e32 v239, 0xffff0000, v184
	v_pk_fma_f32 v[110:111], v[110:111], v[236:237], v[238:239]
	v_lshlrev_b32_e32 v236, 16, v181
	v_and_b32_e32 v237, 0xffff0000, v181
	v_lshlrev_b32_e32 v238, 16, v185
	v_and_b32_e32 v239, 0xffff0000, v185
	v_pk_fma_f32 v[112:113], v[112:113], v[236:237], v[238:239]
	v_lshlrev_b32_e32 v236, 16, v182
	v_and_b32_e32 v237, 0xffff0000, v182
	v_lshlrev_b32_e32 v238, 16, v186
	v_and_b32_e32 v239, 0xffff0000, v186
	v_pk_fma_f32 v[106:107], v[106:107], v[236:237], v[238:239]
	v_lshlrev_b32_e32 v236, 16, v183
	v_and_b32_e32 v237, 0xffff0000, v183
	v_lshlrev_b32_e32 v238, 16, v187
	v_and_b32_e32 v239, 0xffff0000, v187
	v_pk_fma_f32 v[108:109], v[108:109], v[236:237], v[238:239]
	v_cvt_pk_bf16_f32 v110, v110, v111
	v_cvt_pk_bf16_f32 v111, v112, v113
	v_cvt_pk_bf16_f32 v112, v106, v107
	v_cvt_pk_bf16_f32 v113, v108, v109
	v_lshlrev_b32_e32 v236, 16, v188
	v_and_b32_e32 v237, 0xffff0000, v188
	v_lshlrev_b32_e32 v238, 16, v192
	v_and_b32_e32 v239, 0xffff0000, v192
	v_pk_fma_f32 v[102:103], v[102:103], v[236:237], v[238:239]
	v_lshlrev_b32_e32 v236, 16, v189
	v_and_b32_e32 v237, 0xffff0000, v189
	v_lshlrev_b32_e32 v238, 16, v193
	v_and_b32_e32 v239, 0xffff0000, v193
	v_pk_fma_f32 v[104:105], v[104:105], v[236:237], v[238:239]
	v_lshlrev_b32_e32 v236, 16, v190
	v_and_b32_e32 v237, 0xffff0000, v190
	v_lshlrev_b32_e32 v238, 16, v194
	v_and_b32_e32 v239, 0xffff0000, v194
	v_pk_fma_f32 v[98:99], v[98:99], v[236:237], v[238:239]
	v_lshlrev_b32_e32 v236, 16, v191
	v_and_b32_e32 v237, 0xffff0000, v191
	v_lshlrev_b32_e32 v238, 16, v195
	v_and_b32_e32 v239, 0xffff0000, v195
	v_pk_fma_f32 v[100:101], v[100:101], v[236:237], v[238:239]
	v_cvt_pk_bf16_f32 v102, v102, v103
	v_cvt_pk_bf16_f32 v103, v104, v105
	v_cvt_pk_bf16_f32 v104, v98, v99
	v_cvt_pk_bf16_f32 v105, v100, v101
	v_add_u32_e32 v228, 0x20, v142
	v_ashrrev_i32_e32 v229, 31, v228
	v_lshlrev_b64 v[212:213], 12, v[228:229]
	v_lshlrev_b64 v[228:229], 11, v[228:229]
	v_lshl_add_u64 v[212:213], s[84:85], 0, v[212:213]
	v_lshl_add_u64 v[228:229], s[20:21], 0, v[228:229]
	v_lshl_add_u64 v[212:213], v[212:213], 0, v[140:141]
	v_lshl_add_u64 v[228:229], v[228:229], 0, v[140:141]
	v_add_u32_e32 v230, 0x30, v142
	v_ashrrev_i32_e32 v231, 31, v230
	v_lshlrev_b64 v[214:215], 12, v[230:231]
	v_lshlrev_b64 v[230:231], 11, v[230:231]
	v_lshl_add_u64 v[214:215], s[84:85], 0, v[214:215]
	v_lshl_add_u64 v[230:231], s[20:21], 0, v[230:231]
	v_lshl_add_u64 v[214:215], v[214:215], 0, v[140:141]
	v_lshl_add_u64 v[230:231], v[230:231], 0, v[140:141]
	global_load_dwordx4 v[164:167], v[212:213], off
	global_load_dwordx4 v[168:171], v[228:229], off
	global_load_dwordx4 v[172:175], v[212:213], off offset:64
	global_load_dwordx4 v[176:179], v[228:229], off offset:64
	global_load_dwordx4 v[180:183], v[214:215], off
	global_load_dwordx4 v[184:187], v[230:231], off
	global_load_dwordx4 v[188:191], v[214:215], off offset:64
	global_load_dwordx4 v[192:195], v[230:231], off offset:64
	global_store_dwordx4 v[220:221], v[126:129], off
	global_store_dwordx4 v[220:221], v[118:121], off offset:64
	global_store_dwordx4 v[222:223], v[110:113], off
	global_store_dwordx4 v[222:223], v[102:105], off offset:64
	s_waitcnt vmcnt(4)
; __device__ __forceinline__ unsigned cvt_pk_bf16(float lo, float hi) { unsigned r; asm volatile("v_cvt_pk_bf16_f32 %0, %1, %2" : "=v"(r) : "v"(lo), "v"(hi)); return r; }
; __device__ __forceinline__ void st8_bf16(bf16_t* p, f32x4 a, f32x4 b) { u32x4 w; w.x = cvt_pk_bf16(a[0], a[1]); w.y = cvt_pk_bf16(a[2], a[3]); w.z = cvt_pk_bf16(b[0], b[1]); w.w = cvt_pk_bf16(b[2], b[3]); *(u32x4*)p = w; }
;     __device__ __forceinline__ void operator()(AccRef acc, const pg8::Unit& u, int wr, int wc, int fr, int fq) const {
;         const int lc = u.pn * 256 + wc * 64 + fq * 8;
; #pragma unroll
;         for (int ai = 0; ai < 2; ++ai)
; #pragma unroll
;             for (int m = 0; m < 4; ++m) {
;                 const size_t row = (size_t)(u.pm * 256 + ai * 128 + wr * 64 + m * 16 + fr);
; #pragma unroll
;                 for (int bj = 0; bj < 2; ++bj) {
;                     f32x4 g0, g1; ld8_bf16(gate + row * 2048 + lc + bj * 32, g0, g1);
;                     f32x4 v0 = acc[ai][bj][m][0] * g0, v1 = acc[ai][bj][m][1] * g1;
;                     bf16_t* mp = Mb + row * 1024 + lc + bj * 32;
;                     if (ADD) { f32x4 p0, p1; ld8_bf16(mp, p0, p1); v0 += p0; v1 += p1; }
;                     st8_bf16(mp, v0, v1);
;                 }
;             }
;     }
	v_lshlrev_b32_e32 v236, 16, v164
	v_and_b32_e32 v237, 0xffff0000, v164
	v_lshlrev_b32_e32 v238, 16, v168
	v_and_b32_e32 v239, 0xffff0000, v168
	v_pk_fma_f32 v[94:95], v[94:95], v[236:237], v[238:239]
	v_lshlrev_b32_e32 v236, 16, v165
	v_and_b32_e32 v237, 0xffff0000, v165
	v_lshlrev_b32_e32 v238, 16, v169
	v_and_b32_e32 v239, 0xffff0000, v169
	v_pk_fma_f32 v[96:97], v[96:97], v[236:237], v[238:239]
	v_lshlrev_b32_e32 v236, 16, v166
	v_and_b32_e32 v237, 0xffff0000, v166
	v_lshlrev_b32_e32 v238, 16, v170
	v_and_b32_e32 v239, 0xffff0000, v170
	v_pk_fma_f32 v[90:91], v[90:91], v[236:237], v[238:239]
	v_lshlrev_b32_e32 v236, 16, v167
	v_and_b32_e32 v237, 0xffff0000, v167
	v_lshlrev_b32_e32 v238, 16, v171
	v_and_b32_e32 v239, 0xffff0000, v171
	v_pk_fma_f32 v[92:93], v[92:93], v[236:237], v[238:239]
	v_cvt_pk_bf16_f32 v94, v94, v95
	v_cvt_pk_bf16_f32 v95, v96, v97
	v_cvt_pk_bf16_f32 v96, v90, v91
	v_cvt_pk_bf16_f32 v97, v92, v93
	v_lshlrev_b32_e32 v236, 16, v172
	v_and_b32_e32 v237, 0xffff0000, v172
	v_lshlrev_b32_e32 v238, 16, v176
	v_and_b32_e32 v239, 0xffff0000, v176
	v_pk_fma_f32 v[86:87], v[86:87], v[236:237], v[238:239]
	v_lshlrev_b32_e32 v236, 16, v173
	v_and_b32_e32 v237, 0xffff0000, v173
	v_lshlrev_b32_e32 v238, 16, v177
	v_and_b32_e32 v239, 0xffff0000, v177
	v_pk_fma_f32 v[88:89], v[88:89], v[236:237], v[238:239]
	v_lshlrev_b32_e32 v236, 16, v174
	v_and_b32_e32 v237, 0xffff0000, v174
	v_lshlrev_b32_e32 v238, 16, v178
	v_and_b32_e32 v239, 0xffff0000, v178
	v_pk_fma_f32 v[82:83], v[82:83], v[236:237], v[238:239]
	v_lshlrev_b32_e32 v236, 16, v175
	v_and_b32_e32 v237, 0xffff0000, v175
	v_lshlrev_b32_e32 v238, 16, v179
	v_and_b32_e32 v239, 0xffff0000, v179
	v_pk_fma_f32 v[84:85], v[84:85], v[236:237], v[238:239]
	v_cvt_pk_bf16_f32 v86, v86, v87
	v_cvt_pk_bf16_f32 v87, v88, v89
	v_cvt_pk_bf16_f32 v88, v82, v83
	v_cvt_pk_bf16_f32 v89, v84, v85
	v_lshlrev_b32_e32 v236, 16, v180
	v_and_b32_e32 v237, 0xffff0000, v180
	v_lshlrev_b32_e32 v238, 16, v184
	v_and_b32_e32 v239, 0xffff0000, v184
	v_pk_fma_f32 v[78:79], v[78:79], v[236:237], v[238:239]
	v_lshlrev_b32_e32 v236, 16, v181
	v_and_b32_e32 v237, 0xffff0000, v181
	v_lshlrev_b32_e32 v238, 16, v185
	v_and_b32_e32 v239, 0xffff0000, v185
	v_pk_fma_f32 v[80:81], v[80:81], v[236:237], v[238:239]
	v_lshlrev_b32_e32 v236, 16, v182
	v_and_b32_e32 v237, 0xffff0000, v182
	v_lshlrev_b32_e32 v238, 16, v186
	v_and_b32_e32 v239, 0xffff0000, v186
	v_pk_fma_f32 v[74:75], v[74:75], v[236:237], v[238:239]
	v_lshlrev_b32_e32 v236, 16, v183
	v_and_b32_e32 v237, 0xffff0000, v183
	v_lshlrev_b32_e32 v238, 16, v187
	v_and_b32_e32 v239, 0xffff0000, v187
	v_pk_fma_f32 v[76:77], v[76:77], v[236:237], v[238:239]
	v_cvt_pk_bf16_f32 v78, v78, v79
	v_cvt_pk_bf16_f32 v79, v80, v81
	v_cvt_pk_bf16_f32 v80, v74, v75
	v_cvt_pk_bf16_f32 v81, v76, v77
	v_lshlrev_b32_e32 v236, 16, v188
	v_and_b32_e32 v237, 0xffff0000, v188
	v_lshlrev_b32_e32 v238, 16, v192
	v_and_b32_e32 v239, 0xffff0000, v192
	v_pk_fma_f32 v[70:71], v[70:71], v[236:237], v[238:239]
	v_lshlrev_b32_e32 v236, 16, v189
	v_and_b32_e32 v237, 0xffff0000, v189
	v_lshlrev_b32_e32 v238, 16, v193
	v_and_b32_e32 v239, 0xffff0000, v193
	v_pk_fma_f32 v[72:73], v[72:73], v[236:237], v[238:239]
	v_lshlrev_b32_e32 v236, 16, v190
	v_and_b32_e32 v237, 0xffff0000, v190
	v_lshlrev_b32_e32 v238, 16, v194
	v_and_b32_e32 v239, 0xffff0000, v194
	v_pk_fma_f32 v[66:67], v[66:67], v[236:237], v[238:239]
	v_lshlrev_b32_e32 v236, 16, v191
	v_and_b32_e32 v237, 0xffff0000, v191
	v_lshlrev_b32_e32 v238, 16, v195
	v_and_b32_e32 v239, 0xffff0000, v195
	v_pk_fma_f32 v[68:69], v[68:69], v[236:237], v[238:239]
	v_cvt_pk_bf16_f32 v70, v70, v71
	v_cvt_pk_bf16_f32 v71, v72, v73
	v_cvt_pk_bf16_f32 v72, v66, v67
	v_cvt_pk_bf16_f32 v73, v68, v69
	v_add_u32_e32 v220, 0x80, v142
	v_ashrrev_i32_e32 v221, 31, v220
	v_lshlrev_b64 v[212:213], 12, v[220:221]
	v_lshlrev_b64 v[220:221], 11, v[220:221]
	v_lshl_add_u64 v[212:213], s[84:85], 0, v[212:213]
	v_lshl_add_u64 v[220:221], s[20:21], 0, v[220:221]
	v_lshl_add_u64 v[212:213], v[212:213], 0, v[140:141]
	v_lshl_add_u64 v[220:221], v[220:221], 0, v[140:141]
	v_add_u32_e32 v222, 0x90, v142
	v_ashrrev_i32_e32 v223, 31, v222
	v_lshlrev_b64 v[214:215], 12, v[222:223]
	v_lshlrev_b64 v[222:223], 11, v[222:223]
	v_lshl_add_u64 v[214:215], s[84:85], 0, v[214:215]
	v_lshl_add_u64 v[222:223], s[20:21], 0, v[222:223]
	v_lshl_add_u64 v[214:215], v[214:215], 0, v[140:141]
	v_lshl_add_u64 v[222:223], v[222:223], 0, v[140:141]
	global_load_dwordx4 v[164:167], v[212:213], off
	global_load_dwordx4 v[168:171], v[220:221], off
	global_load_dwordx4 v[172:175], v[212:213], off offset:64
	global_load_dwordx4 v[176:179], v[220:221], off offset:64
	global_load_dwordx4 v[180:183], v[214:215], off
	global_load_dwordx4 v[184:187], v[222:223], off
	global_load_dwordx4 v[188:191], v[214:215], off offset:64
	global_load_dwordx4 v[192:195], v[222:223], off offset:64
	global_store_dwordx4 v[228:229], v[94:97], off
	global_store_dwordx4 v[228:229], v[86:89], off offset:64
	global_store_dwordx4 v[230:231], v[78:81], off
	global_store_dwordx4 v[230:231], v[70:73], off offset:64
	s_waitcnt vmcnt(4)
; __device__ __forceinline__ unsigned cvt_pk_bf16(float lo, float hi) { unsigned r; asm volatile("v_cvt_pk_bf16_f32 %0, %1, %2" : "=v"(r) : "v"(lo), "v"(hi)); return r; }
; __device__ __forceinline__ void st8_bf16(bf16_t* p, f32x4 a, f32x4 b) { u32x4 w; w.x = cvt_pk_bf16(a[0], a[1]); w.y = cvt_pk_bf16(a[2], a[3]); w.z = cvt_pk_bf16(b[0], b[1]); w.w = cvt_pk_bf16(b[2], b[3]); *(u32x4*)p = w; }
;     __device__ __forceinline__ void operator()(AccRef acc, const pg8::Unit& u, int wr, int wc, int fr, int fq) const {
;         const int lc = u.pn * 256 + wc * 64 + fq * 8;
; #pragma unroll
;         for (int ai = 0; ai < 2; ++ai)
; #pragma unroll
;             for (int m = 0; m < 4; ++m) {
;                 const size_t row = (size_t)(u.pm * 256 + ai * 128 + wr * 64 + m * 16 + fr);
; #pragma unroll
;                 for (int bj = 0; bj < 2; ++bj) {
;                     f32x4 g0, g1; ld8_bf16(gate + row * 2048 + lc + bj * 32, g0, g1);
;                     f32x4 v0 = acc[ai][bj][m][0] * g0, v1 = acc[ai][bj][m][1] * g1;
;                     bf16_t* mp = Mb + row * 1024 + lc + bj * 32;
;                     if (ADD) { f32x4 p0, p1; ld8_bf16(mp, p0, p1); v0 += p0; v1 += p1; }
;                     st8_bf16(mp, v0, v1);
;                 }
;             }
;     }
	v_lshlrev_b32_e32 v236, 16, v164
	v_and_b32_e32 v237, 0xffff0000, v164
	v_lshlrev_b32_e32 v238, 16, v168
	v_and_b32_e32 v239, 0xffff0000, v168
	v_pk_fma_f32 v[62:63], v[62:63], v[236:237], v[238:239]
	v_lshlrev_b32_e32 v236, 16, v165
	v_and_b32_e32 v237, 0xffff0000, v165
	v_lshlrev_b32_e32 v238, 16, v169
	v_and_b32_e32 v239, 0xffff0000, v169
	v_pk_fma_f32 v[64:65], v[64:65], v[236:237], v[238:239]
	v_lshlrev_b32_e32 v236, 16, v166
	v_and_b32_e32 v237, 0xffff0000, v166
	v_lshlrev_b32_e32 v238, 16, v170
	v_and_b32_e32 v239, 0xffff0000, v170
	v_pk_fma_f32 v[58:59], v[58:59], v[236:237], v[238:239]
	v_lshlrev_b32_e32 v236, 16, v167
	v_and_b32_e32 v237, 0xffff0000, v167
	v_lshlrev_b32_e32 v238, 16, v171
	v_and_b32_e32 v239, 0xffff0000, v171
	v_pk_fma_f32 v[60:61], v[60:61], v[236:237], v[238:239]
	v_cvt_pk_bf16_f32 v62, v62, v63
	v_cvt_pk_bf16_f32 v63, v64, v65
	v_cvt_pk_bf16_f32 v64, v58, v59
	v_cvt_pk_bf16_f32 v65, v60, v61
	v_lshlrev_b32_e32 v236, 16, v172
	v_and_b32_e32 v237, 0xffff0000, v172
	v_lshlrev_b32_e32 v238, 16, v176
	v_and_b32_e32 v239, 0xffff0000, v176
	v_pk_fma_f32 v[54:55], v[54:55], v[236:237], v[238:239]
	v_lshlrev_b32_e32 v236, 16, v173
	v_and_b32_e32 v237, 0xffff0000, v173
	v_lshlrev_b32_e32 v238, 16, v177
	v_and_b32_e32 v239, 0xffff0000, v177
	v_pk_fma_f32 v[56:57], v[56:57], v[236:237], v[238:239]
	v_lshlrev_b32_e32 v236, 16, v174
	v_and_b32_e32 v237, 0xffff0000, v174
	v_lshlrev_b32_e32 v238, 16, v178
	v_and_b32_e32 v239, 0xffff0000, v178
	v_pk_fma_f32 v[50:51], v[50:51], v[236:237], v[238:239]
	v_lshlrev_b32_e32 v236, 16, v175
	v_and_b32_e32 v237, 0xffff0000, v175
	v_lshlrev_b32_e32 v238, 16, v179
	v_and_b32_e32 v239, 0xffff0000, v179
	v_pk_fma_f32 v[52:53], v[52:53], v[236:237], v[238:239]
	v_cvt_pk_bf16_f32 v54, v54, v55
	v_cvt_pk_bf16_f32 v55, v56, v57
	v_cvt_pk_bf16_f32 v56, v50, v51
	v_cvt_pk_bf16_f32 v57, v52, v53
	v_lshlrev_b32_e32 v236, 16, v180
	v_and_b32_e32 v237, 0xffff0000, v180
	v_lshlrev_b32_e32 v238, 16, v184
	v_and_b32_e32 v239, 0xffff0000, v184
	v_pk_fma_f32 v[46:47], v[46:47], v[236:237], v[238:239]
	v_lshlrev_b32_e32 v236, 16, v181
	v_and_b32_e32 v237, 0xffff0000, v181
	v_lshlrev_b32_e32 v238, 16, v185
	v_and_b32_e32 v239, 0xffff0000, v185
	v_pk_fma_f32 v[48:49], v[48:49], v[236:237], v[238:239]
	v_lshlrev_b32_e32 v236, 16, v182
	v_and_b32_e32 v237, 0xffff0000, v182
	v_lshlrev_b32_e32 v238, 16, v186
	v_and_b32_e32 v239, 0xffff0000, v186
	v_pk_fma_f32 v[42:43], v[42:43], v[236:237], v[238:239]
	v_lshlrev_b32_e32 v236, 16, v183
	v_and_b32_e32 v237, 0xffff0000, v183
	v_lshlrev_b32_e32 v238, 16, v187
	v_and_b32_e32 v239, 0xffff0000, v187
	v_pk_fma_f32 v[44:45], v[44:45], v[236:237], v[238:239]
	v_cvt_pk_bf16_f32 v46, v46, v47
	v_cvt_pk_bf16_f32 v47, v48, v49
	v_cvt_pk_bf16_f32 v48, v42, v43
	v_cvt_pk_bf16_f32 v49, v44, v45
	v_lshlrev_b32_e32 v236, 16, v188
	v_and_b32_e32 v237, 0xffff0000, v188
	v_lshlrev_b32_e32 v238, 16, v192
	v_and_b32_e32 v239, 0xffff0000, v192
	v_pk_fma_f32 v[38:39], v[38:39], v[236:237], v[238:239]
	v_lshlrev_b32_e32 v236, 16, v189
	v_and_b32_e32 v237, 0xffff0000, v189
	v_lshlrev_b32_e32 v238, 16, v193
	v_and_b32_e32 v239, 0xffff0000, v193
	v_pk_fma_f32 v[40:41], v[40:41], v[236:237], v[238:239]
	v_lshlrev_b32_e32 v236, 16, v190
	v_and_b32_e32 v237, 0xffff0000, v190
	v_lshlrev_b32_e32 v238, 16, v194
	v_and_b32_e32 v239, 0xffff0000, v194
	v_pk_fma_f32 v[34:35], v[34:35], v[236:237], v[238:239]
	v_lshlrev_b32_e32 v236, 16, v191
	v_and_b32_e32 v237, 0xffff0000, v191
	v_lshlrev_b32_e32 v238, 16, v195
	v_and_b32_e32 v239, 0xffff0000, v195
	v_pk_fma_f32 v[36:37], v[36:37], v[236:237], v[238:239]
	v_cvt_pk_bf16_f32 v38, v38, v39
	v_cvt_pk_bf16_f32 v39, v40, v41
	v_cvt_pk_bf16_f32 v40, v34, v35
	v_cvt_pk_bf16_f32 v41, v36, v37
	v_add_u32_e32 v228, 0xa0, v142
	v_ashrrev_i32_e32 v229, 31, v228
	v_lshlrev_b64 v[212:213], 12, v[228:229]
	v_lshlrev_b64 v[228:229], 11, v[228:229]
	v_lshl_add_u64 v[212:213], s[84:85], 0, v[212:213]
	v_lshl_add_u64 v[228:229], s[20:21], 0, v[228:229]
	v_lshl_add_u64 v[212:213], v[212:213], 0, v[140:141]
	v_lshl_add_u64 v[228:229], v[228:229], 0, v[140:141]
	v_add_u32_e32 v230, 0xb0, v142
	v_ashrrev_i32_e32 v231, 31, v230
	v_lshlrev_b64 v[214:215], 12, v[230:231]
	v_lshlrev_b64 v[230:231], 11, v[230:231]
	v_lshl_add_u64 v[214:215], s[84:85], 0, v[214:215]
	v_lshl_add_u64 v[230:231], s[20:21], 0, v[230:231]
	v_lshl_add_u64 v[214:215], v[214:215], 0, v[140:141]
	v_lshl_add_u64 v[230:231], v[230:231], 0, v[140:141]
	global_load_dwordx4 v[164:167], v[212:213], off
	global_load_dwordx4 v[168:171], v[228:229], off
	global_load_dwordx4 v[172:175], v[212:213], off offset:64
	global_load_dwordx4 v[176:179], v[228:229], off offset:64
	global_load_dwordx4 v[180:183], v[214:215], off
	global_load_dwordx4 v[184:187], v[230:231], off
	global_load_dwordx4 v[188:191], v[214:215], off offset:64
	global_load_dwordx4 v[192:195], v[230:231], off offset:64
	global_store_dwordx4 v[220:221], v[62:65], off
	global_store_dwordx4 v[220:221], v[54:57], off offset:64
	global_store_dwordx4 v[222:223], v[46:49], off
	global_store_dwordx4 v[222:223], v[38:41], off offset:64
	s_waitcnt vmcnt(4)
; __device__ __forceinline__ unsigned cvt_pk_bf16(float lo, float hi) { unsigned r; asm volatile("v_cvt_pk_bf16_f32 %0, %1, %2" : "=v"(r) : "v"(lo), "v"(hi)); return r; }
; __device__ __forceinline__ void st8_bf16(bf16_t* p, f32x4 a, f32x4 b) { u32x4 w; w.x = cvt_pk_bf16(a[0], a[1]); w.y = cvt_pk_bf16(a[2], a[3]); w.z = cvt_pk_bf16(b[0], b[1]); w.w = cvt_pk_bf16(b[2], b[3]); *(u32x4*)p = w; }
;     __device__ __forceinline__ void operator()(AccRef acc, const pg8::Unit& u, int wr, int wc, int fr, int fq) const {
;         const int lc = u.pn * 256 + wc * 64 + fq * 8;
; #pragma unroll
;         for (int ai = 0; ai < 2; ++ai)
; #pragma unroll
;             for (int m = 0; m < 4; ++m) {
;                 const size_t row = (size_t)(u.pm * 256 + ai * 128 + wr * 64 + m * 16 + fr);
; #pragma unroll
;                 for (int bj = 0; bj < 2; ++bj) {
;                     f32x4 g0, g1; ld8_bf16(gate + row * 2048 + lc + bj * 32, g0, g1);
;                     f32x4 v0 = acc[ai][bj][m][0] * g0, v1 = acc[ai][bj][m][1] * g1;
;                     bf16_t* mp = Mb + row * 1024 + lc + bj * 32;
;                     if (ADD) { f32x4 p0, p1; ld8_bf16(mp, p0, p1); v0 += p0; v1 += p1; }
;                     st8_bf16(mp, v0, v1);
;                 }
;             }
;     }
	v_lshlrev_b32_e32 v236, 16, v164
	v_and_b32_e32 v237, 0xffff0000, v164
	v_lshlrev_b32_e32 v238, 16, v168
	v_and_b32_e32 v239, 0xffff0000, v168
	v_pk_fma_f32 v[30:31], v[30:31], v[236:237], v[238:239]
	v_lshlrev_b32_e32 v236, 16, v165
	v_and_b32_e32 v237, 0xffff0000, v165
	v_lshlrev_b32_e32 v238, 16, v169
	v_and_b32_e32 v239, 0xffff0000, v169
	v_pk_fma_f32 v[32:33], v[32:33], v[236:237], v[238:239]
	v_lshlrev_b32_e32 v236, 16, v166
	v_and_b32_e32 v237, 0xffff0000, v166
	v_lshlrev_b32_e32 v238, 16, v170
	v_and_b32_e32 v239, 0xffff0000, v170
	v_pk_fma_f32 v[26:27], v[26:27], v[236:237], v[238:239]
	v_lshlrev_b32_e32 v236, 16, v167
	v_and_b32_e32 v237, 0xffff0000, v167
	v_lshlrev_b32_e32 v238, 16, v171
	v_and_b32_e32 v239, 0xffff0000, v171
	v_pk_fma_f32 v[28:29], v[28:29], v[236:237], v[238:239]
	v_cvt_pk_bf16_f32 v30, v30, v31
	v_cvt_pk_bf16_f32 v31, v32, v33
	v_cvt_pk_bf16_f32 v32, v26, v27
	v_cvt_pk_bf16_f32 v33, v28, v29
	v_lshlrev_b32_e32 v236, 16, v172
	v_and_b32_e32 v237, 0xffff0000, v172
	v_lshlrev_b32_e32 v238, 16, v176
	v_and_b32_e32 v239, 0xffff0000, v176
	v_pk_fma_f32 v[22:23], v[22:23], v[236:237], v[238:239]
	v_lshlrev_b32_e32 v236, 16, v173
	v_and_b32_e32 v237, 0xffff0000, v173
	v_lshlrev_b32_e32 v238, 16, v177
	v_and_b32_e32 v239, 0xffff0000, v177
	v_pk_fma_f32 v[24:25], v[24:25], v[236:237], v[238:239]
	v_lshlrev_b32_e32 v236, 16, v174
	v_and_b32_e32 v237, 0xffff0000, v174
	v_lshlrev_b32_e32 v238, 16, v178
	v_and_b32_e32 v239, 0xffff0000, v178
	v_pk_fma_f32 v[18:19], v[18:19], v[236:237], v[238:239]
	v_lshlrev_b32_e32 v236, 16, v175
	v_and_b32_e32 v237, 0xffff0000, v175
	v_lshlrev_b32_e32 v238, 16, v179
	v_and_b32_e32 v239, 0xffff0000, v179
	v_pk_fma_f32 v[20:21], v[20:21], v[236:237], v[238:239]
	v_cvt_pk_bf16_f32 v22, v22, v23
	v_cvt_pk_bf16_f32 v23, v24, v25
	v_cvt_pk_bf16_f32 v24, v18, v19
	v_cvt_pk_bf16_f32 v25, v20, v21
	v_lshlrev_b32_e32 v236, 16, v180
	v_and_b32_e32 v237, 0xffff0000, v180
	v_lshlrev_b32_e32 v238, 16, v184
	v_and_b32_e32 v239, 0xffff0000, v184
	v_pk_fma_f32 v[14:15], v[14:15], v[236:237], v[238:239]
	v_lshlrev_b32_e32 v236, 16, v181
	v_and_b32_e32 v237, 0xffff0000, v181
	v_lshlrev_b32_e32 v238, 16, v185
	v_and_b32_e32 v239, 0xffff0000, v185
	v_pk_fma_f32 v[16:17], v[16:17], v[236:237], v[238:239]
	v_lshlrev_b32_e32 v236, 16, v182
	v_and_b32_e32 v237, 0xffff0000, v182
	v_lshlrev_b32_e32 v238, 16, v186
	v_and_b32_e32 v239, 0xffff0000, v186
	v_pk_fma_f32 v[10:11], v[10:11], v[236:237], v[238:239]
	v_lshlrev_b32_e32 v236, 16, v183
	v_and_b32_e32 v237, 0xffff0000, v183
	v_lshlrev_b32_e32 v238, 16, v187
	v_and_b32_e32 v239, 0xffff0000, v187
	v_pk_fma_f32 v[12:13], v[12:13], v[236:237], v[238:239]
	v_cvt_pk_bf16_f32 v14, v14, v15
	v_cvt_pk_bf16_f32 v15, v16, v17
	v_cvt_pk_bf16_f32 v16, v10, v11
	v_cvt_pk_bf16_f32 v17, v12, v13
	v_lshlrev_b32_e32 v236, 16, v188
	v_and_b32_e32 v237, 0xffff0000, v188
	v_lshlrev_b32_e32 v238, 16, v192
	v_and_b32_e32 v239, 0xffff0000, v192
	v_pk_fma_f32 v[6:7], v[6:7], v[236:237], v[238:239]
	v_lshlrev_b32_e32 v236, 16, v189
	v_and_b32_e32 v237, 0xffff0000, v189
	v_lshlrev_b32_e32 v238, 16, v193
	v_and_b32_e32 v239, 0xffff0000, v193
	v_pk_fma_f32 v[8:9], v[8:9], v[236:237], v[238:239]
	v_lshlrev_b32_e32 v236, 16, v190
	v_and_b32_e32 v237, 0xffff0000, v190
	v_lshlrev_b32_e32 v238, 16, v194
	v_and_b32_e32 v239, 0xffff0000, v194
	v_pk_fma_f32 v[2:3], v[2:3], v[236:237], v[238:239]
	v_lshlrev_b32_e32 v236, 16, v191
	v_and_b32_e32 v237, 0xffff0000, v191
	v_lshlrev_b32_e32 v238, 16, v195
	v_and_b32_e32 v239, 0xffff0000, v195
	v_pk_fma_f32 v[4:5], v[4:5], v[236:237], v[238:239]
	v_cvt_pk_bf16_f32 v6, v6, v7
	v_cvt_pk_bf16_f32 v7, v8, v9
	v_cvt_pk_bf16_f32 v8, v2, v3
	v_cvt_pk_bf16_f32 v9, v4, v5
	global_store_dwordx4 v[228:229], v[30:33], off
	global_store_dwordx4 v[228:229], v[22:25], off offset:64
	global_store_dwordx4 v[230:231], v[14:17], off
	global_store_dwordx4 v[230:231], v[6:9], off offset:64
	s_cbranch_vccnz .LBB0_510
	s_andn2_b64 vcc, exec, s[0:1]
	s_cbranch_vccnz .LBB0_509
	s_barrier
	s_branch .LBB0_509
